# P2: the nine E3 parameter loads issued right after E1's own loads land (instead of at the end of E1)
# baseline (speedup 1.0000x reference)
; __device__ __forceinline__ unsigned pk2(float lo, float hi) { f32x2_t v = {lo, hi}; bf16x2_t b = __builtin_convertvector(v, bf16x2_t); return __builtin_bit_cast(unsigned, b); }
; __device__ __forceinline__ float bflo(unsigned v) { return __uint_as_float(v << 16); }
; __device__ __forceinline__ float bfhi(unsigned v) { return __uint_as_float(v & 0xffff0000u); }
; __device__ __forceinline__ float fexp(float x) { return __builtin_amdgcn_exp2f(x * 1.44269504088896f); }
; __device__ void rwkv_prep_item(const Params& p, char* lds_, int item, PrepRaw& raw, int next_item) {
;     ...
;     for (int q = 0; q < 2; ++q) {
;       pdb[q] = *(const f32x4*)(p.decay_bias + cbp + 4 * q); pib[q] = *(const f32x4*)(p.iclr_bias + cbp + 4 * q);
;       pkk[q] = *(const f32x4*)(p.k_k + cbp + 4 * q); pka[q] = *(const f32x4*)(p.k_a + cbp + 4 * q); prk[q] = *(const f32x4*)(p.r_k + cbp + 4 * q);
;     }
;     ...
;     auto ldshift = [&](int col, float (&o)[8], const u32x4 cur) {
;       u32x4 prv; prv.x = prv.y = prv.z = prv.w = 0u;
;       if (hasprev) prv = *(const u32x4*)(prow - PBW + col);
;       const f32x4 m0 = *(const f32x4*)(p.shift_mu + col), m1 = *(const f32x4*)(p.shift_mu + col + 4);
;       const unsigned cw[4] = {cur.x, cur.y, cur.z, cur.w}, pw[4] = {prv.x, prv.y, prv.z, prv.w};
; #pragma unroll
;       for (int q = 0; q < 4; ++q) {
;         const float c0 = bflo(cw[q]), c1 = bfhi(cw[q]), p0 = bflo(pw[q]), p1 = bfhi(pw[q]);
;         const float mu0 = (q < 2) ? m0[2 * q] : m1[2 * q - 4], mu1 = (q < 2) ? m0[2 * q + 1] : m1[2 * q - 3];
;         o[2 * q] = c0 + (p0 - c0) * mu0;
;         o[2 * q + 1] = c1 + (p1 - c1) * mu1;
;       }
;     };
;     ldshift(hd * 64 + cg8, rr, raw.cur[0]);
;     ldshift(512 + hd * 64 + cg8, kk_, raw.cur[1]);
;     ldshift(1024 + hd * 64 + cg8, vv, raw.cur[2]);
;     float wd[8], ad[8];
;     ldshift(1536 + cg8, wd, raw.cur[3]);
;     ldshift(1600 + cg8, ad, raw.cur[4]);
;     u32x4 w;
;     float th[8];
; #pragma unroll
;     for (int e = 0; e < 8; ++e) th[e] = 1.f - 2.f * __builtin_amdgcn_rcpf(1.f + fexp(2.f * wd[e]));
;     w.x = pk2(th[0], th[1]); w.y = pk2(th[2], th[3]); w.z = pk2(th[4], th[5]); w.w = pk2(th[6], th[7]);
.LBB0_291:
	s_or_b64 exec, exec, s[56:57]
	s_waitcnt vmcnt(6)
	v_lshlrev_b32_e32 v118, 16, v10
	v_and_b32_e32 v155, 0xffff0000, v10
	s_waitcnt vmcnt(0) lgkmcnt(0)
	v_lshlrev_b32_e32 v156, 16, v102
	v_and_b32_e32 v102, 0xffff0000, v102
	v_sub_f32_e32 v156, v156, v118
	v_sub_f32_e32 v102, v102, v155
	s_waitcnt vmcnt(0)
	v_or_b32_e32 v58, s55, v116
	v_lshlrev_b32_e32 v58, 2, v58
	global_load_dwordx4 v[34:37], v58, s[62:63] offset:16
	global_load_dwordx4 v[38:41], v58, s[62:63]
	global_load_dwordx4 v[54:57], v58, s[80:81] offset:16
	global_load_dwordx4 v[70:73], v58, s[80:81]
	global_load_dwordx4 v[46:49], v58, s[64:65] offset:16
	global_load_dwordx4 v[50:53], v58, s[66:67] offset:16
	global_load_dwordx4 v[62:65], v58, s[66:67]
	global_load_dwordx4 v[42:45], v58, s[82:83] offset:16
	global_load_dwordx4 v[58:61], v58, s[82:83]
	v_fmac_f32_e32 v118, v110, v156
	v_fmac_f32_e32 v155, v111, v102
	v_lshlrev_b32_e32 v110, 16, v11
	v_lshlrev_b32_e32 v102, 16, v103
	v_and_b32_e32 v111, 0xffff0000, v11
	v_and_b32_e32 v103, 0xffff0000, v103
	v_sub_f32_e32 v102, v102, v110
	v_fmac_f32_e32 v110, v112, v102
	v_sub_f32_e32 v102, v103, v111
	v_fmac_f32_e32 v111, v113, v102
	v_lshlrev_b32_e32 v112, 16, v12
	v_lshlrev_b32_e32 v102, 16, v104
	v_and_b32_e32 v113, 0xffff0000, v12
	v_and_b32_e32 v103, 0xffff0000, v104
	v_sub_f32_e32 v102, v102, v112
	v_fmac_f32_e32 v112, v106, v102
	v_sub_f32_e32 v102, v103, v113
	v_fmac_f32_e32 v113, v107, v102
	v_and_b32_e32 v102, 0xffff0000, v105
	v_and_b32_e32 v156, 0xffff0000, v13
	v_sub_f32_e32 v102, v102, v156
	v_lshlrev_b32_e32 v103, 16, v105
	v_lshlrev_b32_e32 v157, 16, v13
	v_fmac_f32_e32 v156, v109, v102
	v_and_b32_e32 v104, 0xffff0000, v2
	v_lshlrev_b32_e32 v102, 16, v90
	v_and_b32_e32 v90, 0xffff0000, v90
	v_sub_f32_e32 v103, v103, v157
	v_lshlrev_b32_e32 v105, 16, v2
	v_sub_f32_e32 v90, v90, v104
	v_fmac_f32_e32 v157, v108, v103
	v_sub_f32_e32 v102, v102, v105
	v_fmac_f32_e32 v104, v99, v90
	v_lshlrev_b32_e32 v103, 16, v3
	v_lshlrev_b32_e32 v90, 16, v91
	v_fmac_f32_e32 v105, v98, v102
	v_and_b32_e32 v102, 0xffff0000, v3
	v_and_b32_e32 v91, 0xffff0000, v91
	v_sub_f32_e32 v90, v90, v103
	v_fmac_f32_e32 v103, v100, v90
	v_sub_f32_e32 v90, v91, v102
	v_fmac_f32_e32 v102, v101, v90
	v_lshlrev_b32_e32 v99, 16, v4
	v_lshlrev_b32_e32 v90, 16, v92
	v_and_b32_e32 v98, 0xffff0000, v4
	v_and_b32_e32 v91, 0xffff0000, v92
	v_sub_f32_e32 v90, v90, v99
	v_fmac_f32_e32 v99, v94, v90
	v_sub_f32_e32 v90, v91, v98
	v_fmac_f32_e32 v98, v95, v90
	v_and_b32_e32 v90, 0xffff0000, v93
	v_and_b32_e32 v92, 0xffff0000, v5
	v_lshlrev_b32_e32 v91, 16, v93
	v_lshlrev_b32_e32 v93, 16, v5
	v_sub_f32_e32 v90, v90, v92
	v_sub_f32_e32 v91, v91, v93
	v_fmac_f32_e32 v92, v97, v90
	v_and_b32_e32 v90, 0xffff0000, v6
	v_lshlrev_b32_e32 v94, 16, v78
	v_and_b32_e32 v78, 0xffff0000, v78
	v_fmac_f32_e32 v93, v96, v91
	v_lshlrev_b32_e32 v91, 16, v6
	v_sub_f32_e32 v78, v78, v90
	v_sub_f32_e32 v94, v94, v91
	v_fmac_f32_e32 v90, v87, v78
	v_lshlrev_b32_e32 v87, 16, v7
	v_lshlrev_b32_e32 v78, 16, v79
	v_fmac_f32_e32 v91, v86, v94
	v_and_b32_e32 v86, 0xffff0000, v7
	v_and_b32_e32 v79, 0xffff0000, v79
	v_sub_f32_e32 v78, v78, v87
	v_fmac_f32_e32 v87, v88, v78
	v_sub_f32_e32 v78, v79, v86
	v_fmac_f32_e32 v86, v89, v78
	v_lshlrev_b32_e32 v89, 16, v8
	v_lshlrev_b32_e32 v78, 16, v80
	v_and_b32_e32 v88, 0xffff0000, v8
	v_and_b32_e32 v79, 0xffff0000, v80
	v_sub_f32_e32 v78, v78, v89
	v_fmac_f32_e32 v89, v78, v82
	v_sub_f32_e32 v78, v79, v88
	v_fmac_f32_e32 v88, v78, v83
	v_and_b32_e32 v78, 0xffff0000, v81
	v_lshlrev_b32_e32 v79, 16, v81
	v_and_b32_e32 v82, 0xffff0000, v9
	v_lshlrev_b32_e32 v83, 16, v9
	v_sub_f32_e32 v79, v79, v83
	v_sub_f32_e32 v78, v78, v82
	v_fmac_f32_e32 v83, v79, v84
	v_fmac_f32_e32 v82, v78, v85
	v_add_f32_e32 v84, v118, v118
	v_add_f32_e32 v85, v155, v155
	v_add_f32_e32 v100, v110, v110
	v_add_f32_e32 v101, v111, v111
	v_add_f32_e32 v106, v112, v112
	v_add_f32_e32 v107, v113, v113
	v_add_f32_e32 v108, v157, v157
	v_add_f32_e32 v109, v156, v156
	v_mul_f32_e32 v84, 0x3fb8aa3b, v84
	v_mul_f32_e32 v85, 0x3fb8aa3b, v85
	v_mul_f32_e32 v100, 0x3fb8aa3b, v100
	v_mul_f32_e32 v101, 0x3fb8aa3b, v101
	v_mul_f32_e32 v106, 0x3fb8aa3b, v106
	v_mul_f32_e32 v107, 0x3fb8aa3b, v107
	v_mul_f32_e32 v108, 0x3fb8aa3b, v108
	v_mul_f32_e32 v109, 0x3fb8aa3b, v109
	v_exp_f32_e32 v84, v84
	v_exp_f32_e32 v85, v85
	v_exp_f32_e32 v100, v100
	v_exp_f32_e32 v101, v101
	v_exp_f32_e32 v106, v106
	v_exp_f32_e32 v107, v107
	v_exp_f32_e32 v108, v108
	v_exp_f32_e32 v109, v109
	v_lshlrev_b32_e32 v110, 16, v14
	v_and_b32_e32 v111, 0xffff0000, v14
	v_lshlrev_b32_e32 v112, 16, v74
	v_and_b32_e32 v113, 0xffff0000, v74
	v_pk_add_f32 v[112:113], v[112:113], v[110:111] neg_lo:[0,1] neg_hi:[0,1]
	v_add_f32_e32 v84, 1.0, v84
	v_add_f32_e32 v85, 1.0, v85
	v_add_f32_e32 v100, 1.0, v100
	v_add_f32_e32 v101, 1.0, v101
	v_add_f32_e32 v106, 1.0, v106
	v_add_f32_e32 v107, 1.0, v107
	v_add_f32_e32 v108, 1.0, v108
	v_add_f32_e32 v109, 1.0, v109
	v_lshlrev_b32_e32 v74, 16, v75
	v_and_b32_e32 v75, 0xffff0000, v75
	v_rcp_f32_e32 v84, v84
	v_rcp_f32_e32 v85, v85
	v_rcp_f32_e32 v100, v100
	v_rcp_f32_e32 v101, v101
	v_rcp_f32_e32 v106, v106
	v_rcp_f32_e32 v107, v107
	v_rcp_f32_e32 v108, v108
	v_rcp_f32_e32 v109, v109
	v_pk_fma_f32 v[84:85], v[84:85], 2.0, 1.0 op_sel_hi:[1,0,0] neg_lo:[1,0,0] neg_hi:[1,0,0]
	v_pk_fma_f32 v[100:101], v[100:101], 2.0, 1.0 op_sel_hi:[1,0,0] neg_lo:[1,0,0] neg_hi:[1,0,0]
	v_pk_fma_f32 v[106:107], v[106:107], 2.0, 1.0 op_sel_hi:[1,0,0] neg_lo:[1,0,0] neg_hi:[1,0,0]
	v_pk_fma_f32 v[108:109], v[108:109], 2.0, 1.0 op_sel_hi:[1,0,0] neg_lo:[1,0,0] neg_hi:[1,0,0]
	v_add_lshl_u32 v118, s55, v240, 7
; __device__ __forceinline__ unsigned pk2(float lo, float hi) { f32x2_t v = {lo, hi}; bf16x2_t b = __builtin_convertvector(v, bf16x2_t); return __builtin_bit_cast(unsigned, b); }
; __device__ void rwkv_prep_item(const Params& p, char* lds_, int item, PrepRaw& raw, int next_item) {
;     ...
;     w.x = pk2(th[0], th[1]); w.y = pk2(th[2], th[3]); w.z = pk2(th[4], th[5]); w.w = pk2(th[6], th[7]);
;     *(u32x4*)(TW + t * LD + cg8) = w;
;     w.x = pk2(ad[0], ad[1]); w.y = pk2(ad[2], ad[3]); w.z = pk2(ad[4], ad[5]); w.w = pk2(ad[6], ad[7]);
;     *(u32x4*)(AD + t * LD + cg8) = w;
;     *(u32x4*)(DUs + t * LD + cg8) = *(const u32x4*)(p.DUt + (size_t)(hd * 64 + t) * 64 + cg8);
;     *(u32x4*)(IUs + t * LD + cg8) = *(const u32x4*)(p.IUt + (size_t)(hd * 64 + t) * 64 + cg8);
;   }
;   __syncthreads();
;   const int it = wave >> 1, jt0 = (wave & 1) * 2, mr = lane & 15, mg = lane >> 4;
;   const int mi = it * 16 + mr;
;   {
;     f32x4 a1[2], a2[2]; zero2(a1); zero2(a2);
;     mm_nt(TW, DUs, a1, wave, lane);
;     mm_nt(AD, IUs, a2, wave, lane);
; #pragma unroll
;     for (int jj = 0; jj < 2; ++jj) {
;       *(f32x4*)(Zw + mi * 68 + (jt0 + jj) * 16 + 4 * mg) = a1[jj];
;       *(f32x4*)(Za + mi * 68 + (jt0 + jj) * 16 + 4 * mg) = a2[jj];
;     }
;   }
;   __syncthreads();
	v_mul_f32_e32 v67, v67, v104
	v_mul_f32_e32 v66, v66, v105
	v_mul_f32_e32 v68, v68, v103
	v_mul_f32_e32 v69, v69, v102
	s_add_i32 s90, s54, s50
	v_pk_fma_f32 v[94:95], v[200:201], v[112:113], v[110:111]
	v_lshlrev_b32_e32 v110, 16, v15
	v_and_b32_e32 v111, 0xffff0000, v15
	v_pk_add_f32 v[74:75], v[74:75], v[110:111] neg_lo:[0,1] neg_hi:[0,1]
	s_nop 0
	v_pk_fma_f32 v[96:97], v[202:203], v[74:75], v[110:111]
	v_lshlrev_b32_e32 v74, 16, v16
	v_and_b32_e32 v75, 0xffff0000, v16
	v_lshlrev_b32_e32 v110, 16, v76
	v_and_b32_e32 v111, 0xffff0000, v76
	v_pk_add_f32 v[110:111], v[110:111], v[74:75] neg_lo:[0,1] neg_hi:[0,1]
	v_lshlrev_b32_e32 v76, 16, v17
	v_pk_fma_f32 v[78:79], v[192:193], v[110:111], v[74:75]
	v_lshlrev_b32_e32 v74, 16, v77
	v_and_b32_e32 v75, 0xffff0000, v77
	v_and_b32_e32 v77, 0xffff0000, v17
	v_pk_add_f32 v[74:75], v[74:75], v[76:77] neg_lo:[0,1] neg_hi:[0,1]
	s_nop 0
	v_pk_fma_f32 v[80:81], v[194:195], v[74:75], v[76:77]
	v_cvt_pk_bf16_f32 v74, v84, v85
	v_cvt_pk_bf16_f32 v75, v100, v101
	v_cvt_pk_bf16_f32 v76, v106, v107
	v_cvt_pk_bf16_f32 v77, v108, v109
	ds_write_b128 v117, v[74:77]
	v_cvt_pk_bf16_f32 v74, v94, v95
	v_cvt_pk_bf16_f32 v75, v96, v97
	v_cvt_pk_bf16_f32 v76, v78, v79
	v_cvt_pk_bf16_f32 v77, v80, v81
	ds_write_b128 v117, v[74:77] offset:9216
	v_mul_f32_e32 v85, v67, v67
	v_fmac_f32_e32 v85, v66, v66
	v_fmac_f32_e32 v85, v68, v68
	v_fmac_f32_e32 v85, v69, v69
	ds_write_b128 v117, v[158:161] offset:18432
	ds_write_b128 v117, v[196:199] offset:27648
	s_and_b32 s94, s90, 0x1c0
	v_add_lshl_u32 v196, s94, v240, 7
	v_mov_b32_e32 v197, 0
	v_mov_b64_e32 v[158:159], v[196:197]
	v_lshl_add_u64 v[196:197], v[136:137], 0, v[196:197]
	global_load_dwordx4 v[196:199], v[196:197], off
	v_lshl_add_u64 v[158:159], v[134:135], 0, v[158:159]
	global_load_dwordx4 v[158:161], v[158:159], off
	s_waitcnt lgkmcnt(0)
	s_barrier
	ds_read_b128 v[74:77], v162
	ds_read_b128 v[78:81], v163
	ds_read_b128 v[94:97], v163 offset:2304
	s_waitcnt lgkmcnt(1)
	v_mfma_f32_16x16x32_bf16 v[78:81], v[78:81], v[74:77], 0
	s_waitcnt lgkmcnt(0)
	v_mfma_f32_16x16x32_bf16 v[74:77], v[94:97], v[74:77], 0
	ds_read_b128 v[94:97], v162 offset:64
	ds_read_b128 v[106:109], v164
	s_waitcnt lgkmcnt(0)
	v_mfma_f32_16x16x32_bf16 v[78:81], v[106:109], v[94:97], v[78:81]
	ds_read_b128 v[106:109], v165 offset:2304
	s_waitcnt lgkmcnt(0)
	v_mfma_f32_16x16x32_bf16 v[74:77], v[106:109], v[94:97], v[74:77]
	ds_read_b128 v[94:97], v166
	ds_read_b128 v[106:109], v167
	ds_read_b128 v[110:113], v167 offset:2304
	s_waitcnt lgkmcnt(1)
	v_mfma_f32_16x16x32_bf16 v[106:109], v[106:109], v[94:97], 0
	s_waitcnt lgkmcnt(0)
	v_mfma_f32_16x16x32_bf16 v[94:97], v[110:113], v[94:97], 0
	ds_read_b128 v[110:113], v166 offset:64
	ds_read_b128 v[192:195], v168
	s_waitcnt lgkmcnt(0)
	v_mfma_f32_16x16x32_bf16 v[106:109], v[192:195], v[110:113], v[106:109]
	ds_read_b128 v[192:195], v169 offset:2304
	s_waitcnt lgkmcnt(0)
	v_mfma_f32_16x16x32_bf16 v[94:97], v[192:195], v[110:113], v[94:97]
	ds_write_b128 v170, v[78:81]
	s_nop 3
	ds_write_b128 v171, v[106:109]
	ds_write_b128 v170, v[74:77] offset:64
	s_nop 0
	ds_write_b128 v171, v[94:97] offset:64
	s_waitcnt lgkmcnt(0)
	s_barrier
; __device__ __forceinline__ float fsigmoid(float x) { return __builtin_amdgcn_rcpf(1.f + fexp(-x)); }
; __device__ void rwkv_prep_item(const Params& p, char* lds_, int item, PrepRaw& raw, int next_item) {
;     ...
;   float av[8], bv[8], k2[8], lw[8];
;   float bon;
;   {
;     float ss = 0.f; bon = 0.f;
;     float kk[8], ai[8];
; #pragma unroll
;     for (int e = 0; e < 8; ++e) {
;       const float zw = Zw[t * 68 + cg8 + e] + pdb[e >> 2][e & 3];
;       const float za = Za[t * 68 + cg8 + e] + pib[e >> 2][e & 3];
;       lw[e] = -0.6065306597126334f * fsigmoid(zw);
;       ai[e] = fsigmoid(za);
;       kk[e] = kk_[e] * pkk[e >> 2][e & 3];
;       k2[e] = kk_[e] * (1.f + (ai[e] - 1.f) * pka[e >> 2][e & 3]);
;       ss += kk[e] * kk[e];
;       bon += rr[e] * k2[e] * prk[e >> 2][e & 3];
;     }
;     ss += __shfl_xor(ss, 1); ss += __shfl_xor(ss, 2); ss += __shfl_xor(ss, 4);
;     bon += __shfl_xor(bon, 1); bon += __shfl_xor(bon, 2); bon += __shfl_xor(bon, 4);
;     const float inv = __builtin_amdgcn_rsqf(fmaxf(ss, 1e-24f));
; #pragma unroll
;     for (int e = 0; e < 8; ++e) { const float kn = kk[e] * inv; av[e] = -kn; bv[e] = kn * ai[e]; }
;   }
;   __builtin_amdgcn_sched_barrier(0);
;   if (next_item < 4096) prep_load(p, next_item, raw);
	ds_read_b128 v[74:77], v172
	ds_read_b128 v[78:81], v173
	s_waitcnt vmcnt(0) lgkmcnt(0)
	v_add_f32_e32 v70, v70, v78
	v_mul_f32_e32 v70, 0xbfb8aa3b, v70
	v_exp_f32_e32 v70, v70
	s_nop 0
	v_add_f32_e32 v70, 1.0, v70
	v_rcp_f32_e32 v70, v70
	s_nop 0
	v_add_f32_e32 v78, -1.0, v70
	v_fma_f32 v62, v62, v78, 1.0
	v_mul_f32_e32 v62, v105, v62
	v_mul_f32_e32 v78, v91, v62
	v_fma_f32 v84, v58, v78, 0
	v_add_f32_e32 v58, v71, v79
	v_mul_f32_e32 v58, 0xbfb8aa3b, v58
	v_exp_f32_e32 v58, v58
	s_nop 0
	v_add_f32_e32 v58, 1.0, v58
	v_rcp_f32_e32 v71, v58
	s_nop 0
	v_add_f32_e32 v58, -1.0, v71
	v_fma_f32 v58, v63, v58, 1.0
	v_mul_f32_e32 v63, v104, v58
	v_mul_f32_e32 v58, v90, v63
	v_fmac_f32_e32 v84, v59, v58
	v_add_f32_e32 v58, v72, v80
	v_mul_f32_e32 v58, 0xbfb8aa3b, v58
	v_exp_f32_e32 v58, v58
	s_nop 0
	v_add_f32_e32 v58, 1.0, v58
	v_rcp_f32_e32 v72, v58
	s_nop 0
	v_add_f32_e32 v58, -1.0, v72
	v_fma_f32 v58, v64, v58, 1.0
	v_mul_f32_e32 v64, v103, v58
	v_mul_f32_e32 v58, v87, v64
	v_fmac_f32_e32 v84, v60, v58
	v_add_f32_e32 v58, v73, v81
	v_mul_f32_e32 v58, 0xbfb8aa3b, v58
	v_exp_f32_e32 v58, v58
	s_nop 0
	v_add_f32_e32 v58, 1.0, v58
	v_rcp_f32_e32 v73, v58
	s_nop 0
	v_add_f32_e32 v58, -1.0, v73
	v_fma_f32 v58, v65, v58, 1.0
	v_mul_f32_e32 v65, v102, v58
	v_mul_f32_e32 v58, v86, v65
	v_fmac_f32_e32 v84, v61, v58
	ds_read_b128 v[58:61], v176
	ds_read_b128 v[78:81], v177
	s_waitcnt lgkmcnt(0)
	v_add_f32_e32 v54, v54, v78
	v_mul_f32_e32 v54, 0xbfb8aa3b, v54
	v_exp_f32_e32 v54, v54
	v_mul_f32_e32 v78, v46, v99
	v_fmac_f32_e32 v85, v78, v78
	v_add_f32_e32 v54, 1.0, v54
	v_rcp_f32_e32 v54, v54
	s_nop 0
	v_add_f32_e32 v46, -1.0, v54
	v_fma_f32 v46, v50, v46, 1.0
	v_mul_f32_e32 v46, v99, v46
	v_mul_f32_e32 v50, v89, v46
	v_fmac_f32_e32 v84, v42, v50
	v_add_f32_e32 v42, v55, v79
	v_mul_f32_e32 v42, 0xbfb8aa3b, v42
	v_exp_f32_e32 v42, v42
	v_mul_f32_e32 v55, v47, v98
	v_fmac_f32_e32 v85, v55, v55
	v_mul_f32_e32 v79, v49, v92
	v_add_f32_e32 v42, 1.0, v42
	v_rcp_f32_e32 v50, v42
	s_nop 0
	v_add_f32_e32 v42, -1.0, v50
	v_fma_f32 v42, v51, v42, 1.0
	v_mul_f32_e32 v47, v98, v42
	v_mul_f32_e32 v42, v88, v47
	v_fmac_f32_e32 v84, v43, v42
	v_add_f32_e32 v42, v56, v80
	v_mul_f32_e32 v42, 0xbfb8aa3b, v42
	v_exp_f32_e32 v42, v42
	v_mul_f32_e32 v56, v48, v93
	v_fmac_f32_e32 v85, v56, v56
	v_fmac_f32_e32 v85, v79, v79
	v_add_f32_e32 v42, 1.0, v42
	v_rcp_f32_e32 v51, v42
	s_nop 0
	v_add_f32_e32 v42, -1.0, v51
	v_fma_f32 v42, v52, v42, 1.0
	v_mul_f32_e32 v52, v93, v42
	v_mul_f32_e32 v42, v83, v52
	v_fmac_f32_e32 v84, v44, v42
	v_add_f32_e32 v42, v57, v81
	v_mul_f32_e32 v42, 0xbfb8aa3b, v42
	v_exp_f32_e32 v42, v42
	s_nop 0
	v_add_f32_e32 v42, 1.0, v42
	v_rcp_f32_e32 v57, v42
	s_nop 0
	v_add_f32_e32 v42, -1.0, v57
	v_fma_f32 v42, v53, v42, 1.0
	v_mul_f32_e32 v53, v92, v42
	v_mul_f32_e32 v42, v82, v53
	v_fmac_f32_e32 v84, v45, v42
	ds_bpermute_b32 v42, v178, v85
	s_waitcnt lgkmcnt(0)
	v_add_f32_e32 v42, v85, v42
	ds_bpermute_b32 v43, v179, v42
	s_waitcnt lgkmcnt(0)
	v_add_f32_e32 v80, v42, v43
	ds_bpermute_b32 v42, v178, v84
	ds_bpermute_b32 v81, v180, v80
	s_waitcnt lgkmcnt(1)
	v_add_f32_e32 v42, v84, v42
	ds_bpermute_b32 v43, v179, v42
	s_waitcnt lgkmcnt(0)
	v_add_f32_e32 v48, v42, v43
	ds_bpermute_b32 v49, v180, v48
	s_cmpk_gt_i32 s90, 0xfff
	s_cselect_b64 s[56:57], -1, 0
	v_mov_b64_e32 v[44:45], v[20:21]
	s_and_b64 vcc, exec, s[56:57]
	v_mov_b64_e32 v[42:43], v[18:19]
	s_cbranch_vccnz .LBB0_293
	s_ashr_i32 s58, s90, 9
	s_lshl_b32 s74, s90, 6
	s_ashr_i32 s59, s58, 31
	s_and_b32 s74, s74, 0xfc0
	s_lshl_b64 s[58:59], s[58:59], 12
	v_add_u32_e32 v118, s74, v240
	v_lshl_add_u64 v[2:3], s[58:59], 0, v[118:119]
	v_mov_b64_e32 v[4:5], s[78:79]
	s_and_b32 s55, s90, 0x1c0
	v_mad_u64_u32 v[10:11], s[58:59], v2, s53, v[4:5]
	v_mad_i32_i24 v11, v3, s53, v11
	s_lshl_b32 s74, s55, 1
	v_lshl_add_u64 v[2:3], v[10:11], 0, s[74:75]
	v_mov_b32_e32 v155, v119
	v_lshl_add_u64 v[12:13], v[2:3], 0, v[154:155]
	v_lshl_add_u64 v[14:15], v[10:11], 0, v[154:155]
	global_load_dwordx4 v[6:9], v[12:13], off
	global_load_dwordx4 v[2:5], v[12:13], off offset:1024
	global_load_dwordx4 v[42:45], v[12:13], off offset:2048
	s_nop 0
	global_load_dwordx4 v[10:13], v[14:15], off offset:3072
	s_nop 0
	global_load_dwordx4 v[14:17], v[14:15], off offset:3200
